# all seams: the L1 invalidate of the acquire is issued right after the arrive so it overlaps the barrier latency (no wave of the CU loads through the L1 until release)
# speedup vs baseline: 1.0091x; 1.0091x over previous
.Lxb1_census_done:
	v_readfirstlane_b32 s98, v28
	s_mov_b32 s42, 0
	global_atomic_add v6, v4, v5, s[34:35] sc0
	buffer_inv sc1
	s_mul_i32 s33, s86, 1
	s_mul_i32 s39, s98, 1
	s_waitcnt vmcnt(0)
	v_readfirstlane_b32 s38, v6
	v_mov_b32_e32 v7, s98
	s_add_i32 s38, s38, 1
	s_cmp_lg_u32 s38, s39
	s_cbranch_scc1 .Lxb1_spin
	buffer_wbl2 sc1
	s_waitcnt vmcnt(0)
	global_atomic_add v22, v7, s[40:41]
.Lxb1_spin:
	global_load_dword v8, v22, s[40:41] sc1
	s_waitcnt vmcnt(0)
	v_cmp_le_u32_e32 vcc, s33, v8
	s_cbranch_vccnz .Lxb1_done
	s_add_i32 s42, s42, 1
	s_cmp_lt_u32 s42, 0x400000
	s_cbranch_scc0 .Lxb1_done
	s_sleep 1
	s_branch .Lxb1_spin
.Lxb1_done:
	s_waitcnt vmcnt(0)
.LBB0_164:
	s_or_b64 exec, exec, s[0:1]
	v_mov_b32_e32 v8, v176
	s_cmpk_lt_i32 s54, 0x600
	s_waitcnt lgkmcnt(0)
	s_barrier
	s_mov_b32 s101, 0
	s_bitcmp1_b32 s54, 3
	s_cbranch_scc0 .Lin_big
	s_mov_b32 s101, 1
	v_readlane_b32 s64, v252, 6
	v_readlane_b32 s65, v252, 7
	s_add_u32 s64, s64, 0x20000
	s_addc_u32 s65, s65, 0
	s_branch .LBB0_294

.Lin_seam2:
	s_waitcnt vmcnt(0)
	s_barrier
	s_mov_b64 s[0:1], exec
	v_readlane_b32 s2, v252, 9
	v_readlane_b32 s3, v252, 10
	s_and_b64 s[2:3], s[0:1], s[2:3]
	s_mov_b64 exec, s[2:3]
	s_cbranch_execz .LBB0_359
	v_readlane_b32 s30, v252, 11
	v_readlane_b32 s31, v252, 12
	v_readlane_b32 s32, v252, 13
	v_mov_b32_e32 v5, 1
	v_mov_b32_e32 v22, 0
	s_add_u32 s34, s30, 0x1400
	s_addc_u32 s35, s31, 0
	s_lshl_b32 s32, s32, 8
	s_add_u32 s40, s30, 0x3400
	s_addc_u32 s41, s31, 0
	v_mov_b32_e32 v4, s32
	s_mov_b32 s42, 0
	s_and_b32 s36, s54, 63
	s_lshl_b32 s36, s36, 2
	s_addk_i32 s36, 0x3800
	v_mov_b32_e32 v9, s36
	global_load_dword v10, v9, s[30:31] sc1
	global_load_dword v11, v9, s[30:31] offset:256 sc1
	global_load_dword v12, v9, s[30:31] offset:512 sc1
	global_load_dword v13, v9, s[30:31] offset:768 sc1
	global_atomic_add v6, v4, v5, s[34:35] sc0
	buffer_inv sc1
	s_mul_i32 s33, s86, 2
	s_mul_i32 s39, s98, 2
	s_waitcnt vmcnt(0)
	v_readfirstlane_b32 s38, v6
	v_readfirstlane_b32 s36, v10
	v_readfirstlane_b32 s37, v11
	v_readfirstlane_b32 s43, v12
	v_readfirstlane_b32 s44, v13
	s_cmp_lg_u32 s36, s37
	s_cselect_b32 s99, 1, 0
	s_cmp_lg_u32 s36, s43
	s_cselect_b32 s37, 1, 0
	s_or_b32 s99, s99, s37
	s_cmp_lg_u32 s36, s44
	s_cselect_b32 s37, 1, 0
	s_or_b32 s99, s99, s37
	s_cmp_eq_u32 s36, 0
	s_cselect_b32 s37, 1, 0
	s_or_b32 s99, s99, s37
	v_mov_b32_e32 v7, s98
	s_add_i32 s38, s38, 1
	s_cmp_lg_u32 s38, s39
	s_cbranch_scc1 .Lxb2_spin
	buffer_wbl2 sc1
	s_waitcnt vmcnt(0)
	global_atomic_add v22, v7, s[40:41]
.Lxb2_spin:
	global_load_dword v8, v22, s[40:41] sc1
	s_waitcnt vmcnt(0)
	v_cmp_le_u32_e32 vcc, s33, v8
	s_cbranch_vccnz .Lxb2_done
	s_add_i32 s42, s42, 1
	s_cmp_lt_u32 s42, 0x400000
	s_cbranch_scc0 .Lxb2_done
	s_sleep 1
	s_branch .Lxb2_spin
.Lxb2_done:
	s_waitcnt vmcnt(0)
.LBB0_359:
	s_or_b64 exec, exec, s[0:1]
	v_writelane_b32 v252, s64, 46
	s_mov_b32 s0, s54
	s_cmpk_gt_i32 s54, 0x7f
	v_writelane_b32 v252, s65, 47
	v_writelane_b32 v252, s0, 48
	s_waitcnt lgkmcnt(0)
	s_barrier
	v_writelane_b32 v252, s1, 49
	s_cbranch_scc1 .LBB0_371
	v_readlane_b32 s0, v252, 0
	v_readlane_b32 s4, v252, 4
	v_readlane_b32 s5, v252, 5
	s_add_u32 s0, s4, 0x40f8000
	v_readlane_b32 s1, v252, 1
	v_readlane_b32 s2, v252, 2
	v_readlane_b32 s3, v252, 3
	v_readlane_b32 s6, v252, 6
	v_readlane_b32 s7, v252, 7
	v_writelane_b32 v252, s0, 50
	s_addc_u32 s0, s5, 0
	v_writelane_b32 v252, s0, 51
	s_add_u32 s0, s6, 0x3140000
	v_writelane_b32 v252, s0, 52
	s_addc_u32 s0, s7, 0
	s_add_u32 s89, s6, 0x4160000
	v_writelane_b32 v252, s0, 53
	s_addc_u32 s0, s7, 0
	v_writelane_b32 v252, s0, 54
	s_add_u32 s0, s6, 0x5180000
	v_writelane_b32 v252, s0, 55
	s_addc_u32 s0, s7, 0
	v_writelane_b32 v252, s0, 56
	s_add_u32 s0, s6, 0x71c0000
	v_writelane_b32 v252, s0, 57
	s_addc_u32 s0, s7, 0
	v_writelane_b32 v252, s0, 58
	s_add_i32 s74, 0, 0x1dc00
	v_readlane_b32 s0, v252, 48
	v_mov_b32_e32 v77, 0
	s_mov_b32 s75, 0xc2fc0000
	v_mov_b32_e32 v122, 0x42800000
	v_mov_b32_e32 v123, 0x42000000
	s_add_i32 s90, 0, 0x11000
	s_movk_i32 s85, 0x110
	s_add_i32 s91, 0, 0x19800
	v_not_b32_e32 v124, 63
	s_mov_b32 s2, 0xffff0000
	s_mov_b32 s33, 0xffff
	s_mov_b64 s[94:95], 0x40000
	s_mov_b64 s[96:97], 0x20000
	v_mbcnt_hi_u32_b32 v125, -1, v139
	s_mov_b32 s84, s0
	v_readlane_b32 s1, v252, 49
	s_branch .LBB0_362

.LBB0_610:
	s_waitcnt vmcnt(0)
	s_barrier
	s_mov_b64 s[0:1], exec
	v_readlane_b32 s2, v252, 9
	v_readlane_b32 s3, v252, 10
	s_and_b64 s[2:3], s[0:1], s[2:3]
	s_mov_b64 exec, s[2:3]
	s_cbranch_execz .LBB0_662
	v_readlane_b32 s30, v252, 11
	v_readlane_b32 s31, v252, 12
	v_readlane_b32 s32, v252, 13
	v_mov_b32_e32 v5, 1
	v_mov_b32_e32 v22, 0
	s_add_u32 s34, s30, 0x1400
	s_addc_u32 s35, s31, 0
	s_lshl_b32 s32, s32, 8
	s_add_u32 s40, s30, 0x3400
	s_addc_u32 s41, s31, 0
	v_mov_b32_e32 v4, s32
	s_mov_b32 s42, 0
	global_atomic_add v6, v4, v5, s[34:35] sc0
	buffer_inv sc1
	s_mul_i32 s33, s86, 3
	s_mul_i32 s39, s98, 3
	s_waitcnt vmcnt(0)
	v_readfirstlane_b32 s38, v6
	v_mov_b32_e32 v7, s98
	s_add_i32 s38, s38, 1
	s_cmp_lg_u32 s38, s39
	s_cbranch_scc1 .Lxb3_spin
	buffer_wbl2 sc1
	s_waitcnt vmcnt(0)
	global_atomic_add v22, v7, s[40:41]
.Lxb3_spin:
	global_load_dword v8, v22, s[40:41] sc1
	s_waitcnt vmcnt(0)
	v_cmp_le_u32_e32 vcc, s33, v8
	s_cbranch_vccnz .Lxb3_done
	s_add_i32 s42, s42, 1
	s_cmp_lt_u32 s42, 0x400000
	s_cbranch_scc0 .Lxb3_done
	s_sleep 1
	s_branch .Lxb3_spin
.Lxb3_done:
	s_waitcnt vmcnt(0)
.LBB0_662:
	s_or_b64 exec, exec, s[0:1]
	v_mov_b32_e32 v8, v176
	s_cmpk_lt_i32 s72, 0x100
	s_waitcnt lgkmcnt(0)
	s_barrier
	s_cselect_b64 s[0:1], -1, 0
	s_cmpk_gt_i32 s72, 0xff
	v_readfirstlane_b32 s10, v8
	s_cbranch_scc1 .LBB0_686
	s_ashr_i32 s2, s72, 31
	s_lshr_b32 s3, s2, 29
	s_add_i32 s3, s72, s3
	s_and_b32 s4, s3, -8
	s_sub_i32 s7, s72, s4
	s_cmp_gt_i32 s7, -1
	s_cbranch_scc0 .LBB0_665
	s_lshl_b32 s6, s7, 5
	s_cbranch_execz .LBB0_666
	s_branch .LBB0_667

.Lxb4_nowb:
	global_atomic_add v4, v5, s[34:35]
	buffer_inv sc1
	s_mov_b32 s42, 0

.Lxb4_acq:
	s_waitcnt vmcnt(0)
	s_branch .Lxb4_end
.Lxb4_global:
	v_readlane_b32 s30, v252, 11
	v_readlane_b32 s31, v252, 12
	v_readlane_b32 s32, v252, 13
	v_mov_b32_e32 v5, 1
	v_mov_b32_e32 v22, 0
	s_add_u32 s34, s30, 0x1400
	s_addc_u32 s35, s31, 0
	s_lshl_b32 s32, s32, 8
	s_add_u32 s40, s30, 0x3400
	s_addc_u32 s41, s31, 0
	v_mov_b32_e32 v4, s32
	s_mov_b32 s42, 0
	global_atomic_add v6, v4, v5, s[34:35] sc0
	buffer_inv sc1
	s_mul_i32 s33, s86, 4
	s_mul_i32 s39, s98, 4
	s_waitcnt vmcnt(0)
	v_readfirstlane_b32 s38, v6
	v_mov_b32_e32 v7, s98
	s_add_i32 s38, s38, 1
	s_cmp_lg_u32 s38, s39
	s_cbranch_scc1 .Lxb4_spin
	buffer_wbl2 sc1
	s_waitcnt vmcnt(0)
	global_atomic_add v22, v7, s[40:41]
.Lxb4_spin:
	global_load_dword v8, v22, s[40:41] sc1
	s_waitcnt vmcnt(0)
	v_cmp_le_u32_e32 vcc, s33, v8
	s_cbranch_vccnz .Lxb4_done
	s_add_i32 s42, s42, 1
	s_cmp_lt_u32 s42, 0x400000
	s_cbranch_scc0 .Lxb4_done
	s_sleep 1
	s_branch .Lxb4_spin
.Lxb4_done:
	s_waitcnt vmcnt(0)
.Lxb4_end:
.LBB0_776:
	s_or_b64 exec, exec, s[0:1]
	v_readlane_b32 s8, v252, 0
	v_readlane_b32 s9, v252, 1
	v_readlane_b32 s10, v252, 2
	v_readlane_b32 s11, v252, 3
	v_readlane_b32 s12, v252, 4
	v_readlane_b32 s13, v252, 5
	v_readlane_b32 s14, v252, 6
	v_readlane_b32 s15, v252, 7
	s_mov_b64 s[8:9], s[12:13]
	s_mov_b64 s[10:11], s[14:15]
	s_add_u32 s3, s10, 0xb240000
	v_mov_b32_e32 v178, v176
	s_waitcnt lgkmcnt(0)
	s_barrier
	s_addc_u32 s38, s11, 0
	s_and_b64 vcc, exec, s[4:5]
	v_readfirstlane_b32 s11, v178
	s_cbranch_vccnz .LBB0_869
	s_ashr_i32 s39, s72, 31
	s_lshr_b32 s0, s39, 29
	s_add_i32 s2, s72, s0
	s_and_b32 s0, s2, -8
	s_sub_i32 s7, s72, s0
	s_cmp_gt_i32 s7, -1
	s_cbranch_scc0 .LBB0_779
	s_lshl_b32 s6, s7, 5
	s_cbranch_execz .LBB0_780
	s_branch .LBB0_781

.Lxb5_global:
	v_readlane_b32 s30, v252, 11
	v_readlane_b32 s31, v252, 12
	v_readlane_b32 s32, v252, 13
	v_mov_b32_e32 v5, 1
	v_mov_b32_e32 v22, 0
	s_add_u32 s34, s30, 0x1400
	s_addc_u32 s35, s31, 0
	s_lshl_b32 s32, s32, 8
	s_add_u32 s40, s30, 0x3400
	s_addc_u32 s41, s31, 0
	v_mov_b32_e32 v4, s32
	s_mov_b32 s42, 0
	global_atomic_add v6, v4, v5, s[34:35] sc0
	buffer_inv sc1
	s_mul_i32 s33, s86, 5
	s_mul_i32 s39, s98, 5
	s_waitcnt vmcnt(0)
	v_readfirstlane_b32 s38, v6
	v_mov_b32_e32 v7, s98
	s_add_i32 s38, s38, 1
	s_cmp_lg_u32 s38, s39
	s_cbranch_scc1 .Lxb5_spin
	buffer_wbl2 sc1
	s_waitcnt vmcnt(0)
	global_atomic_add v22, v7, s[40:41]
.Lxb5_spin:
	global_load_dword v8, v22, s[40:41] sc1
	s_waitcnt vmcnt(0)
	v_cmp_le_u32_e32 vcc, s33, v8
	s_cbranch_vccnz .Lxb5_done
	s_add_i32 s42, s42, 1
	s_cmp_lt_u32 s42, 0x400000
	s_cbranch_scc0 .Lxb5_done
	s_sleep 1
	s_branch .Lxb5_spin
.Lxb5_done:
	s_waitcnt vmcnt(0)
.Lxb5_end:
.LBB0_1060:
	s_mov_b32 s100, 0
	s_or_b64 exec, exec, s[0:1]
	v_readlane_b32 s8, v252, 0
	v_readlane_b32 s9, v252, 1
	v_readlane_b32 s10, v252, 2
	v_readlane_b32 s11, v252, 3
	v_readlane_b32 s12, v252, 4
	v_readlane_b32 s13, v252, 5
	v_readlane_b32 s14, v252, 6
	v_readlane_b32 s15, v252, 7
	s_mov_b64 s[8:9], s[12:13]
	s_mov_b64 s[10:11], s[14:15]
	s_add_u32 s8, s10, 0x4160000
	s_addc_u32 s9, s11, 0
	v_mov_b32_e32 v9, v176
	s_waitcnt lgkmcnt(0)
	s_barrier
	s_cmpk_gt_i32 s72, 0x3ff
	v_readfirstlane_b32 s7, v9
	s_cbranch_scc1 .LBB0_1086
	s_ashr_i32 s2, s72, 31
	s_lshr_b32 s0, s2, 29
	s_add_i32 s3, s72, s0
	s_and_b32 s0, s3, -8
	s_sub_i32 s10, s72, s0
	s_cmp_gt_i32 s10, -1
	s_cbranch_scc0 .LBB0_1063
	s_lshl_b32 s6, s10, 7
	s_cbranch_execz .LBB0_1064
	s_branch .LBB0_1065

.Lxb6_global:
	v_readlane_b32 s30, v252, 11
	v_readlane_b32 s31, v252, 12
	v_readlane_b32 s32, v252, 13
	v_mov_b32_e32 v5, 1
	v_mov_b32_e32 v22, 0
	s_add_u32 s34, s30, 0x1400
	s_addc_u32 s35, s31, 0
	s_lshl_b32 s32, s32, 8
	s_add_u32 s40, s30, 0x3400
	s_addc_u32 s41, s31, 0
	v_mov_b32_e32 v4, s32
	s_mov_b32 s42, 0
	global_atomic_add v6, v4, v5, s[34:35] sc0
	buffer_inv sc1
	s_mul_i32 s33, s86, 6
	s_mul_i32 s39, s98, 6
	s_waitcnt vmcnt(0)
	v_readfirstlane_b32 s38, v6
	v_mov_b32_e32 v7, s98
	s_add_i32 s38, s38, 1
	s_cmp_lg_u32 s38, s39
	s_cbranch_scc1 .Lxb6_spin
	buffer_wbl2 sc1
	s_waitcnt vmcnt(0)
	global_atomic_add v22, v7, s[40:41]
.Lxb6_spin:
	global_load_dword v8, v22, s[40:41] sc1
	s_waitcnt vmcnt(0)
	v_cmp_le_u32_e32 vcc, s33, v8
	s_cbranch_vccnz .Lxb6_done
	s_add_i32 s42, s42, 1
	s_cmp_lt_u32 s42, 0x400000
	s_cbranch_scc0 .Lxb6_done
	s_sleep 1
	s_branch .Lxb6_spin
.Lxb6_done:
	s_waitcnt vmcnt(0)
.Lxb6_end:
.LBB0_1143:
	s_or_b64 exec, exec, s[0:1]
	v_mov_b32_e32 v148, v176
	s_waitcnt lgkmcnt(0)
	s_barrier
	s_and_b64 vcc, exec, s[4:5]
	v_readfirstlane_b32 s33, v148
	s_cbranch_vccnz .LBB0_1218
	s_ashr_i32 s36, s72, 31
	s_lshr_b32 s0, s36, 29
	s_add_i32 s7, s72, s0
	s_and_b32 s0, s7, -8
	s_sub_i32 s6, s72, s0
	s_cmp_gt_i32 s6, -1
	s_cbranch_scc0 .LBB0_1146
	s_lshl_b32 s2, s6, 5
	s_ashr_i32 s0, s7, 3
	s_cbranch_execz .LBB0_1147
	s_branch .LBB0_1148
